# stack + GEMM pipeline fill: K-tile-1 LDS-DMA issued before waiting for K-tile 0 in all seven 256x256 GEMM phases
# baseline (speedup 1.0000x reference)
.LBB1_218:
	v_mov_b32_e32 v133, v113
	v_lshl_add_u64 v[8:9], s[60:61], 0, v[132:133]
	v_mov_b32_e32 v137, v113
	v_and_b32_e32 v7, 48, v0
	v_lshlrev_b32_e32 v16, 6, v0
	s_movk_i32 s19, 0x3c0
	v_lshlrev_b32_e32 v0, 2, v0
	v_lshl_add_u64 v[10:11], s[60:61], 0, v[136:137]
	v_mov_b32_e32 v131, v113
	s_and_b32 s27, s30, 3
	s_lshl_b32 s18, s26, 13
	v_and_or_b32 v7, v16, s19, v7
	v_and_b32_e32 v0, 32, v0
	s_add_i32 m0, s9, 0x18000
	v_lshl_add_u64 v[8:9], v[8:9], 0, s[48:49]
	v_lshl_add_u64 v[12:13], s[40:41], 0, v[130:131]
	v_mov_b32_e32 v135, v113
	s_lshl_b32 s25, s26, 6
	v_bitop3_b32 v16, v7, s18, v0 bitop3:0xde
	s_lshl_b32 s18, s27, 12
	global_load_lds_dwordx4 v[8:9], off
	v_lshl_add_u64 v[8:9], v[10:11], 0, s[48:49]
	s_add_i32 m0, s9, 0x1a000
	s_add_i32 s54, s9, 0x8000
	s_add_i32 s55, s9, 0xa000
	v_lshl_add_u64 v[14:15], s[40:41], 0, v[134:135]
	v_bitop3_b32 v148, v7, s18, v0 bitop3:0xde
	global_load_lds_dwordx4 v[8:9], off
	v_lshl_add_u64 v[8:9], v[12:13], 0, s[48:49]
	s_mov_b32 m0, s54
	s_add_u32 s18, s60, 0x20080
	global_load_lds_dwordx4 v[8:9], off
	v_lshl_add_u64 v[8:9], v[14:15], 0, s[48:49]
	s_mov_b32 m0, s55
	s_addc_u32 s19, s61, 0
	global_load_lds_dwordx4 v[8:9], off
	s_add_i32 m0, s9, 0x1c000
	v_lshl_add_u64 v[8:9], s[18:19], 0, v[132:133]
	global_load_lds_dwordx4 v[8:9], off
	v_lshl_add_u64 v[8:9], s[18:19], 0, v[136:137]
	s_add_i32 m0, s9, 0x1e000
	v_lshlrev_b32_e32 v0, 15, v1
	global_load_lds_dwordx4 v[8:9], off
	v_and_b32_e32 v0, 0xffff0000, v0
	v_lshl_add_u32 v0, v2, 12, v0
	v_and_b32_e32 v1, 1, v1
	v_lshl_or_b32 v0, v1, 6, v0
	v_lshl_add_u32 v138, v3, 1, v0
	v_lshlrev_b32_e32 v0, 15, v4
	v_and_b32_e32 v0, 0xffff0000, v0
	s_waitcnt vmcnt(8)
	s_barrier
	s_waitcnt vmcnt(6)
	v_lshl_add_u32 v0, v5, 12, v0
	v_and_b32_e32 v1, 1, v4
	s_cmp_lt_u32 s30, 4
	v_lshl_or_b32 v0, v1, 6, v0
	s_cselect_b64 s[18:19], -1, 0
	s_lshl_b32 s56, s27, 6
	s_ashr_i32 s57, s1, 31
	v_mov_b32_e32 v139, v113
	v_lshl_add_u32 v140, v6, 1, v0
	v_mov_b32_e32 v141, v113
	s_mov_b32 s66, 0
	v_add_u32_e32 v149, 0, v16
	s_movk_i32 s81, 0xbc
	s_barrier
	s_branch .LBB1_221

.LBB1_385:
	s_sext_i32_i8 s66, s16
	s_lshl_b32 s24, s18, 6
	v_and_b32_e32 v1, 48, v0
	s_lshl_b32 s16, s18, 13
	v_lshlrev_b32_e32 v6, 6, v0
	s_movk_i32 s18, 0x3c0
	v_lshlrev_b32_e32 v0, 2, v0
	s_and_b32 s26, s17, 3
	v_and_or_b32 v1, v6, s18, v1
	v_and_b32_e32 v0, 32, v0
	v_lshl_add_u64 v[2:3], s[38:39], 0, v[112:113]
	v_mov_b32_e32 v135, v113
	v_bitop3_b32 v6, v1, s16, v0 bitop3:0xde
	s_lshl_b32 s16, s26, 12
	v_lshl_add_u64 v[4:5], s[38:39], 0, v[134:135]
	v_bitop3_b32 v136, v1, s16, v0 bitop3:0xde
	s_add_i32 m0, s7, 0x18000
	v_lshl_add_u64 v[0:1], v[2:3], 0, s[48:49]
	v_readlane_b32 s18, v254, 42
	v_mov_b32_e32 v131, v113
	global_load_lds_dwordx4 v[0:1], off
	v_lshl_add_u64 v[0:1], v[4:5], 0, s[48:49]
	s_add_i32 m0, s7, 0x1a000
	v_readlane_b32 s19, v254, 43
	s_add_i32 s25, s7, 0x8000
	v_mov_b32_e32 v133, v113
	global_load_lds_dwordx4 v[0:1], off
	v_lshl_add_u64 v[0:1], s[18:19], 0, v[130:131]
	s_mov_b32 m0, s25
	s_add_i32 s54, s7, 0xa000
	global_load_lds_dwordx4 v[0:1], off
	v_lshl_add_u64 v[0:1], s[18:19], 0, v[132:133]
	s_add_u32 s18, s38, 0xb0080
	s_mov_b32 m0, s54
	s_addc_u32 s19, s39, 0
	global_load_lds_dwordx4 v[0:1], off
	s_add_i32 m0, s7, 0x1c000
	v_lshl_add_u64 v[0:1], s[18:19], 0, v[112:113]
	global_load_lds_dwordx4 v[0:1], off
	v_lshl_add_u64 v[0:1], s[18:19], 0, v[134:135]
	s_add_i32 m0, s7, 0x1e000
	s_cmp_lt_u32 s17, 4
	global_load_lds_dwordx4 v[0:1], off
	s_waitcnt vmcnt(8)
	s_barrier
	s_waitcnt vmcnt(6)
	s_cselect_b64 s[16:17], -1, 0
	s_lshl_b32 s56, s26, 6
	s_mov_b32 s57, 0
	v_add_u32_e32 v137, 0, v6
	s_barrier
	s_branch .LBB1_388

.LBB1_405:
	v_and_b32_e32 v1, 48, v0
	v_lshlrev_b32_e32 v6, 6, v0
	s_movk_i32 s18, 0x3c0
	v_lshlrev_b32_e32 v0, 2, v0
	s_and_b32 s26, s16, 3
	s_lshl_b32 s24, s17, 6
	s_lshl_b32 s17, s17, 13
	v_and_or_b32 v1, v6, s18, v1
	v_and_b32_e32 v0, 32, v0
	v_lshl_add_u64 v[2:3], s[36:37], 0, v[112:113]
	v_mov_b32_e32 v131, v113
	v_bitop3_b32 v6, v1, s17, v0 bitop3:0xde
	s_lshl_b32 s17, s26, 12
	v_lshl_add_u64 v[4:5], s[36:37], 0, v[130:131]
	v_bitop3_b32 v136, v1, s17, v0 bitop3:0xde
	s_add_i32 m0, s7, 0x18000
	v_lshl_add_u64 v[0:1], v[2:3], 0, s[48:49]
	v_readlane_b32 s18, v254, 42
	v_mov_b32_e32 v135, v113
	global_load_lds_dwordx4 v[0:1], off
	v_lshl_add_u64 v[0:1], v[4:5], 0, s[48:49]
	s_add_i32 m0, s7, 0x1a000
	v_readlane_b32 s19, v254, 43
	s_add_i32 s25, s7, 0x8000
	v_mov_b32_e32 v133, v113
	global_load_lds_dwordx4 v[0:1], off
	v_lshl_add_u64 v[0:1], s[18:19], 0, v[134:135]
	s_mov_b32 m0, s25
	s_add_i32 s54, s7, 0xa000
	global_load_lds_dwordx4 v[0:1], off
	v_lshl_add_u64 v[0:1], s[18:19], 0, v[132:133]
	s_add_u32 s18, s36, 0xb0080
	s_mov_b32 m0, s54
	s_addc_u32 s19, s37, 0
	global_load_lds_dwordx4 v[0:1], off
	s_add_i32 m0, s7, 0x1c000
	v_lshl_add_u64 v[0:1], s[18:19], 0, v[112:113]
	global_load_lds_dwordx4 v[0:1], off
	v_lshl_add_u64 v[0:1], s[18:19], 0, v[130:131]
	s_add_i32 m0, s7, 0x1e000
	s_cmp_lt_u32 s16, 4
	global_load_lds_dwordx4 v[0:1], off
	s_waitcnt vmcnt(8)
	s_barrier
	s_waitcnt vmcnt(6)
	v_readlane_b32 s90, v254, 46
	s_cselect_b64 s[16:17], -1, 0
	s_lshl_b32 s55, s26, 6
	s_mov_b32 s56, 0
	v_add_u32_e32 v137, 0, v6
	s_mov_b32 s66, s1
	v_readlane_b32 s91, v254, 47
	s_barrier
	s_branch .LBB1_408

.LBB1_611:
	v_and_b32_e32 v15, 48, v12
	v_lshlrev_b32_e32 v16, 6, v12
	s_movk_i32 s3, 0x3c0
	v_lshlrev_b32_e32 v12, 2, v12
	s_and_b32 s6, s1, 3
	s_lshl_b32 s63, s2, 6
	s_lshl_b32 s2, s2, 13
	v_and_or_b32 v15, v16, s3, v15
	v_and_b32_e32 v12, 32, v12
	s_add_i32 m0, s59, 0x18000
	v_lshl_add_u64 v[4:5], v[4:5], 0, s[48:49]
	v_bitop3_b32 v16, v15, s2, v12 bitop3:0xde
	s_lshl_b32 s2, s6, 12
	global_load_lds_dwordx4 v[4:5], off
	v_lshl_add_u64 v[2:3], v[2:3], 0, s[48:49]
	s_add_i32 m0, s59, 0x1a000
	s_add_i32 s86, s59, 0x8000
	s_add_i32 s87, s59, 0xa000
	v_bitop3_b32 v154, v15, s2, v12 bitop3:0xde
	global_load_lds_dwordx4 v[2:3], off
	v_lshl_add_u64 v[0:1], v[0:1], 0, s[48:49]
	s_mov_b32 m0, s86
	s_add_u32 s2, s18, 0x20080
	global_load_lds_dwordx4 v[0:1], off
	v_lshl_add_u64 v[0:1], v[6:7], 0, s[48:49]
	s_mov_b32 m0, s87
	s_addc_u32 s3, s19, 0
	global_load_lds_dwordx4 v[0:1], off
	s_add_i32 m0, s59, 0x1c000
	v_lshl_add_u64 v[0:1], s[2:3], 0, v[134:135]
	global_load_lds_dwordx4 v[0:1], off
	v_lshl_add_u64 v[0:1], s[2:3], 0, v[138:139]
	s_add_i32 m0, s59, 0x1e000
	s_lshl_b32 s92, s6, 6
	global_load_lds_dwordx4 v[0:1], off
	v_lshlrev_b32_e32 v0, 15, v8
	v_and_b32_e32 v0, 0xffff0000, v0
	v_lshl_add_u32 v0, v9, 12, v0
	v_and_b32_e32 v1, 1, v8
	v_lshl_or_b32 v0, v1, 6, v0
	v_lshl_add_u32 v140, v10, 1, v0
	v_lshlrev_b32_e32 v0, 15, v11
	v_and_b32_e32 v0, 0xffff0000, v0
	s_waitcnt vmcnt(8)
	s_barrier
	s_waitcnt vmcnt(6)
	v_lshl_add_u32 v0, v13, 12, v0
	v_and_b32_e32 v1, 1, v11
	s_cmp_lt_u32 s1, 4
	v_lshl_or_b32 v0, v1, 6, v0
	s_sext_i32_i8 s5, s26
	s_cselect_b64 s[42:43], -1, 0
	v_mov_b32_e32 v141, v113
	v_lshl_add_u32 v142, v14, 1, v0
	v_mov_b32_e32 v143, v113
	s_mov_b32 s93, 0
	v_add_u32_e32 v155, 0, v16
	s_movk_i32 s25, 0x120
	s_barrier
	s_branch .LBB1_614

.LBB1_711:
	s_and_b64 s[26:27], s[26:27], exec
	v_readlane_b32 s26, v255, 41
	v_readlane_b32 s80, v253, 10
	v_readlane_b32 s27, v255, 42
	s_mov_b32 s54, s26
	v_readlane_b32 s81, v253, 11
	v_readlane_b32 s84, v253, 14
	v_readlane_b32 s85, v253, 15
	s_mul_i32 s27, s54, 0x24000
	s_cselect_b32 s43, s81, 0
	s_cselect_b32 s42, s80, 0
	s_cselect_b32 s45, s85, 0
	s_cselect_b32 s44, s84, 0
	s_mul_hi_u32 s26, s26, 0x24000
	s_add_u32 s58, s37, s27
	v_readlane_b32 s27, v253, 52
	s_addc_u32 s59, s27, s26
	s_cmp_lg_u64 s[42:43], 0
	v_and_b32_e32 v15, 48, v8
	v_lshlrev_b32_e32 v16, 6, v8
	s_movk_i32 s27, 0x3c0
	v_lshlrev_b32_e32 v8, 2, v8
	s_cselect_b64 s[60:61], -1, 0
	s_and_b32 s37, s57, 3
	s_lshl_b32 s26, s36, 13
	v_and_or_b32 v15, v16, s27, v15
	v_and_b32_e32 v8, 32, v8
	s_add_i32 m0, s9, 0x18000
	v_lshl_add_u64 v[6:7], v[6:7], 0, s[48:49]
	s_lshl_b32 s54, s36, 6
	v_bitop3_b32 v16, v15, s26, v8 bitop3:0xde
	s_lshl_b32 s26, s37, 12
	global_load_lds_dwordx4 v[6:7], off
	v_lshl_add_u64 v[4:5], v[4:5], 0, s[48:49]
	s_add_i32 m0, s9, 0x1a000
	s_add_i32 s55, s9, 0x8000
	s_add_i32 s56, s9, 0xa000
	v_bitop3_b32 v170, v15, s26, v8 bitop3:0xde
	global_load_lds_dwordx4 v[4:5], off
	v_lshl_add_u64 v[0:1], v[0:1], 0, s[48:49]
	s_mov_b32 m0, s55
	s_add_u32 s26, s52, 0x20080
	global_load_lds_dwordx4 v[0:1], off
	v_lshl_add_u64 v[0:1], v[2:3], 0, s[48:49]
	s_mov_b32 m0, s56
	s_addc_u32 s27, s53, 0
	global_load_lds_dwordx4 v[0:1], off
	s_add_i32 m0, s9, 0x1c000
	v_lshl_add_u64 v[0:1], s[26:27], 0, v[148:149]
	global_load_lds_dwordx4 v[0:1], off
	v_lshl_add_u64 v[0:1], s[26:27], 0, v[152:153]
	s_add_i32 m0, s9, 0x1e000
	v_readlane_b32 s95, v253, 25
	global_load_lds_dwordx4 v[0:1], off
	v_lshlrev_b32_e32 v0, 15, v9
	v_and_b32_e32 v0, 0xffff0000, v0
	v_lshl_add_u32 v0, v10, 12, v0
	v_and_b32_e32 v1, 1, v9
	v_lshl_or_b32 v0, v1, 6, v0
	v_lshl_add_u32 v154, v11, 1, v0
	v_lshlrev_b32_e32 v0, 15, v12
	v_and_b32_e32 v0, 0xffff0000, v0
	s_waitcnt vmcnt(8)
	s_barrier
	s_waitcnt vmcnt(6)
	v_lshl_add_u32 v0, v13, 12, v0
	v_and_b32_e32 v1, 1, v12
	s_cmp_lt_u32 s57, 4
	v_lshl_or_b32 v0, v1, 6, v0
	v_readlane_b32 s64, v255, 27
	s_mov_b32 s25, 0
	s_cselect_b64 s[26:27], -1, 0
	s_lshl_b32 s57, s37, 6
	s_ashr_i32 s66, s1, 31
	v_mov_b32_e32 v155, v113
	v_lshl_add_u32 v156, v14, 1, v0
	v_mov_b32_e32 v157, v113
	v_add_u32_e32 v171, 0, v16
	v_readlane_b32 s65, v255, 28
	v_readlane_b32 s95, v255, 37
	v_readlane_b32 s82, v253, 12
	v_readlane_b32 s83, v253, 13
	v_readlane_b32 s86, v253, 16
	v_readlane_b32 s87, v253, 17
	v_readlane_b32 s88, v253, 18
	v_readlane_b32 s89, v253, 19
	v_readlane_b32 s90, v253, 20
	v_readlane_b32 s91, v253, 21
	v_readlane_b32 s92, v253, 22
	v_readlane_b32 s93, v253, 23
	v_readlane_b32 s94, v253, 24
	s_barrier
	s_branch .LBB1_714

.LBB1_930:
	v_readlane_b32 s16, v255, 41
	v_readlane_b32 s17, v255, 42
	v_readlane_b32 s80, v253, 0
	s_mul_i32 s16, s16, 0x8400
	s_mov_b32 s17, s73
	v_readlane_b32 s82, v253, 2
	v_readlane_b32 s83, v253, 3
	s_lshl_b64 s[16:17], s[16:17], 2
	s_mov_b64 s[54:55], s[82:83]
	s_add_u32 s78, s54, s16
	v_and_b32_e32 v15, 48, v8
	v_lshlrev_b32_e32 v16, 6, v8
	s_movk_i32 s16, 0x3c0
	v_lshlrev_b32_e32 v8, 2, v8
	s_addc_u32 s79, s55, s17
	s_and_b32 s18, s10, 3
	s_lshl_b32 s9, s1, 13
	v_and_or_b32 v15, v16, s16, v15
	v_and_b32_e32 v8, 32, v8
	v_bitop3_b32 v16, v15, s9, v8 bitop3:0xde
	s_lshl_b32 s9, s18, 12
	s_add_i32 m0, s7, 0x18000
	v_lshl_add_u64 v[6:7], v[6:7], 0, s[48:49]
	s_lshr_b32 s89, s72, 3
	s_lshl_b32 s91, s1, 6
	s_lshl_b32 s66, s18, 5
	v_bitop3_b32 v166, v15, s9, v8 bitop3:0xde
	global_load_lds_dwordx4 v[6:7], off
	v_lshl_add_u64 v[4:5], v[4:5], 0, s[48:49]
	s_add_i32 m0, s7, 0x1a000
	s_add_i32 s67, s7, 0x8000
	s_add_i32 s9, s7, 0xa000
	global_load_lds_dwordx4 v[4:5], off
	v_lshl_add_u64 v[0:1], v[0:1], 0, s[48:49]
	s_mov_b32 m0, s67
	s_add_u32 s16, s38, 0x20080
	global_load_lds_dwordx4 v[0:1], off
	v_lshl_add_u64 v[0:1], v[2:3], 0, s[48:49]
	s_mov_b32 m0, s9
	s_addc_u32 s17, s39, 0
	global_load_lds_dwordx4 v[0:1], off
	s_add_i32 m0, s7, 0x1c000
	v_lshl_add_u64 v[0:1], s[16:17], 0, v[156:157]
	global_load_lds_dwordx4 v[0:1], off
	v_lshl_add_u64 v[0:1], s[16:17], 0, v[160:161]
	s_add_i32 m0, s7, 0x1e000
	v_readlane_b32 s81, v253, 1
	global_load_lds_dwordx4 v[0:1], off
	s_cmp_lt_u32 s10, 4
	v_lshlrev_b32_e32 v0, 15, v9
	s_cselect_b64 s[80:81], -1, 0
	s_lshl_b32 s16, s1, 8
	s_lshl_b32 s17, s18, 6
	v_and_b32_e32 v0, 0xffff0000, v0
	s_lshl_b32 s10, s1, 11
	s_or_b32 s54, s17, s16
	v_lshl_add_u32 v0, v10, 12, v0
	v_and_b32_e32 v1, 1, v9
	s_cmp_gt_i32 s1, 0
	v_lshl_or_b32 v0, v1, 6, v0
	v_readlane_b32 s84, v253, 4
	v_readlane_b32 s85, v253, 5
	s_cselect_b64 s[82:83], -1, 0
	s_cmp_lt_i32 s1, 3
	v_lshl_add_u32 v162, v11, 1, v0
	v_lshlrev_b32_e32 v0, 15, v12
	v_readlane_b32 s86, v253, 6
	v_readlane_b32 s87, v253, 7
	s_cselect_b64 s[84:85], -1, 0
	s_cmp_gt_i32 s1, -2
	v_and_b32_e32 v0, 0xffff0000, v0
	s_waitcnt vmcnt(8)
	s_barrier
	s_waitcnt vmcnt(6)
	s_cselect_b64 s[86:87], -1, 0
	s_cmp_lt_i32 s1, 1
	v_lshl_add_u32 v0, v13, 12, v0
	v_and_b32_e32 v1, 1, v12
	s_cselect_b64 s[58:59], -1, 0
	s_add_i32 s10, s10, 0
	v_lshl_or_b32 v0, v1, 6, v0
	s_mov_b32 s55, 0
	s_ashr_i32 s25, s57, 31
	s_add_i32 s90, s10, 0x20400
	s_add_i32 s68, s10, 0x20800
	s_add_i32 s56, s10, 0x20000
	s_add_i32 s10, s10, 0x20200
	v_mov_b32_e32 v163, v113
	v_lshl_add_u32 v164, v14, 1, v0
	v_mov_b32_e32 v165, v113
	v_add_u32_e32 v167, 0, v16
	s_barrier
	s_branch .LBB1_933

.LBB1_1244:
	s_sext_i32_i8 s76, s17
	s_mul_hi_u32 s17, s30, 0x24000
	s_mul_i32 s30, s30, 0x24000
	v_readlane_b32 s31, v253, 51
	s_add_u32 s30, s31, s30
	v_readlane_b32 s31, v253, 52
	s_addc_u32 s31, s31, s17
	v_and_b32_e32 v17, 48, v14
	v_lshlrev_b32_e32 v18, 6, v14
	s_movk_i32 s17, 0x3c0
	v_lshlrev_b32_e32 v14, 2, v14
	s_and_b32 s37, s36, 3
	s_lshl_b32 s54, s16, 6
	s_lshl_b32 s16, s16, 13
	v_and_or_b32 v17, v18, s17, v17
	v_and_b32_e32 v14, 32, v14
	s_add_i32 m0, s10, 0x18000
	v_lshl_add_u64 v[6:7], v[6:7], 0, s[48:49]
	v_bitop3_b32 v18, v17, s16, v14 bitop3:0xde
	s_lshl_b32 s16, s37, 12
	global_load_lds_dwordx4 v[6:7], off
	v_lshl_add_u64 v[4:5], v[4:5], 0, s[48:49]
	s_add_i32 m0, s10, 0x1a000
	s_add_i32 s55, s10, 0x8000
	s_add_i32 s56, s10, 0xa000
	v_bitop3_b32 v146, v17, s16, v14 bitop3:0xde
	global_load_lds_dwordx4 v[4:5], off
	v_lshl_add_u64 v[0:1], v[0:1], 0, s[48:49]
	s_mov_b32 m0, s55
	s_add_u32 s16, s60, 0x58080
	global_load_lds_dwordx4 v[0:1], off
	v_lshl_add_u64 v[0:1], v[2:3], 0, s[48:49]
	s_mov_b32 m0, s56
	s_addc_u32 s17, s61, 0
	global_load_lds_dwordx4 v[0:1], off
	s_add_i32 m0, s10, 0x1c000
	v_lshl_add_u64 v[0:1], s[16:17], 0, v[112:113]
	global_load_lds_dwordx4 v[0:1], off
	v_lshl_add_u64 v[0:1], s[16:17], 0, v[134:135]
	s_add_i32 m0, s10, 0x1e000
	s_movk_i32 s41, 0x1600
	global_load_lds_dwordx4 v[0:1], off
	s_cmp_lt_u32 s36, 4
	v_lshrrev_b32_e32 v1, 1, v8
	v_mul_lo_u32 v0, v10, s41
	s_mov_b32 s40, 0x16000
	s_cselect_b64 s[16:17], -1, 0
	s_lshl_b32 s57, s37, 6
	v_mad_u64_u32 v[0:1], s[36:37], v1, s40, v[0:1]
	v_or_b32_e32 v0, v0, v9
	v_add_lshl_u32 v0, v0, v11, 1
	v_mov_b32_e32 v1, v113
	s_mov_b64 s[42:43], 0x160080
	v_lshl_add_u64 v[136:137], v[0:1], 0, s[42:43]
	v_lshrrev_b32_e32 v1, 1, v12
	v_mul_lo_u32 v0, v15, s41
	v_mad_u64_u32 v[0:1], s[36:37], v1, s40, v[0:1]
	s_waitcnt vmcnt(8)
	s_barrier
	s_waitcnt vmcnt(6)
	v_or_b32_e32 v0, v0, v13
	v_add_lshl_u32 v0, v0, v16, 1
	v_mov_b32_e32 v1, v113
	v_lshl_add_u64 v[138:139], v[0:1], 0, s[42:43]
	s_mov_b32 s66, 0
	v_add_u32_e32 v147, 0, v18
	s_barrier
	s_branch .LBB1_1247
